# v_ntwin with the nt hint removed from the out-proj epilogue residual loads
# baseline (speedup 1.0000x reference)
; #define LAS __attribute__((address_space(3)))
; #define NTLD(p) __builtin_nontemporal_load(p)
;     __device__ __forceinline__ void operator()(const f32x4 (&acc)[2][2][4][2], const pg8::Unit& u, int wr, int wc, int fr, int fq) const {
;     ...
;         const int pm = u.pm; const bool sample = pm >= (MP / 256);
;         const bf16* xb = xbf + (size_t)pm * 256 * DM;
;         float* ob = sample ? out + OUT_YS + (size_t)(pm - MP / 256) * 256 * DM : out + OUT_YP + (size_t)pm * 256 * DM;
;         LAS unsigned char* T = stg + (wr * 4 + wc) * 2048;
;         const int lane = fr + 16 * fq, rr = lane >> 3, p = lane & 7;
;         const int woff0 = fr * 128 + ((fq ^ (fr & 7)) << 4), woff1 = fr * 128 + (((4 + fq) ^ (fr & 7)) << 4);
;         const int roff = rr * 128 + ((p ^ rr) << 4);
;         const int cb = 256 * u.pn + 32 * wc + 4 * p;
; #pragma unroll
;         for (int ai = 0; ai < 2; ++ai) {
;             v4u xv[4][2][2];
; #pragma unroll
;             for (int m = 0; m < 4; ++m) {
;                 const size_t ro = (size_t)(128 * ai + 64 * wr + 16 * m + rr) * DM + (cb & ~7);
; #pragma unroll
;                 for (int bj = 0; bj < 2; ++bj) { xv[m][bj][0] = NTLD((const v4u*)(xb + ro + 128 * bj)); xv[m][bj][1] = NTLD((const v4u*)(xb + ro + 8 * DM + 128 * bj)); }
;             }
; #pragma unroll
;             for (int m = 0; m < 4; ++m) {
;                 const size_t ro = (size_t)(128 * ai + 64 * wr + 16 * m + rr) * DM + cb;
; #pragma unroll
;                 for (int bj = 0; bj < 2; ++bj) {
;                     *(LAS f32x4*)(T + woff0) = acc[ai][bj][m][0]; *(LAS f32x4*)(T + woff1) = acc[ai][bj][m][1];
;                     const f32x4 a0 = *(const LAS f32x4*)(T + roff), a1 = *(const LAS f32x4*)(T + roff + 1024);
;                     const v4u t0 = xv[m][bj][0], t1 = xv[m][bj][1];
;                     const unsigned u0 = (p & 1) ? t0.z : t0.x, u1 = (p & 1) ? t0.w : t0.y, u2 = (p & 1) ? t1.z : t1.x, u3 = (p & 1) ? t1.w : t1.y;
;                     *(f32x4*)(ob + ro + 128 * bj) = (f32x4){bflo(u0), bfhi(u0), bflo(u1), bfhi(u1)} + a0; *(f32x4*)(ob + ro + 8 * DM + 128 * bj) = (f32x4){bflo(u2), bfhi(u2), bflo(u3), bfhi(u3)} + a1;
;                 }
;             }
;         }
.LBB0_1239:
	s_add_i32 s6, s4, 0xffffff00
	s_ashr_i32 s5, s4, 31
	s_lshl_b64 s[22:23], s[6:7], 20
	s_add_u32 s6, s49, s22
	s_addc_u32 s15, s50, s23
	s_lshl_b64 s[22:23], s[4:5], 20
	s_add_u32 s17, s56, s22
	s_addc_u32 s22, s57, s23
	s_cmpk_gt_i32 s4, 0xff
	s_cselect_b32 s15, s15, s22
	s_cselect_b32 s6, s6, s17
	s_lshl_b64 s[4:5], s[4:5], 19
	v_mov_b32_e32 v134, v172
	v_mov_b32_e32 v135, v173
	s_add_u32 s4, s41, s4
	s_addc_u32 s5, s42, s5
	v_lshl_add_u32 v128, v135, 4, v134
	s_lshl_b32 s17, s58, 8
	v_ashrrev_i32_e32 v136, 3, v128
	v_and_b32_e32 v128, 7, v134
	s_or_b32 s17, s17, s44
	v_lshlrev_b32_e32 v137, 2, v128
	v_mov_b32_e32 v128, s17
	v_add_u32_e32 v166, s43, v136
	v_bitop3_b32 v128, v137, s54, v128 bitop3:0xc8
	v_ashrrev_i32_e32 v129, 31, v128
	v_ashrrev_i32_e32 v167, 31, v166
	v_lshl_add_u64 v[168:169], v[128:129], 1, s[4:5]
	v_lshlrev_b64 v[128:129], 11, v[166:167]
	v_lshl_add_u64 v[128:129], v[168:169], 0, v[128:129]
	global_load_dwordx4 v[182:185], v[128:129], off
	global_load_dwordx4 v[190:193], v[128:129], off offset:256
	v_add_co_u32_e32 v130, vcc, s40, v128
	v_or_b32_e32 v128, s17, v137
	s_nop 0
	v_addc_co_u32_e32 v131, vcc, 0, v129, vcc
	global_load_dwordx4 v[186:189], v[130:131], off
	global_load_dwordx4 v[194:197], v[130:131], off offset:256
	v_add_u32_e32 v222, 16, v166
	v_mov_b32_e32 v132, s6
	v_mov_b32_e32 v133, s15
	v_ashrrev_i32_e32 v129, 31, v128
	v_ashrrev_i32_e32 v223, 31, v222
	v_bitop3_b32 v138, v134, v135, 7 bitop3:0x6c
	v_add_u32_e32 v135, 4, v135
	v_lshl_add_u64 v[164:165], v[128:129], 2, v[132:133]
	v_lshlrev_b64 v[128:129], 11, v[222:223]
	v_bitop3_b32 v135, v135, v134, 7 bitop3:0x78
	v_lshl_add_u32 v130, v134, 7, s51
	v_lshl_add_u64 v[128:129], v[168:169], 0, v[128:129]
	v_lshl_add_u32 v179, v138, 4, v130
	v_lshl_add_u32 v180, v135, 4, v130
	v_add_co_u32_e32 v130, vcc, s40, v128
	v_add_u32_e32 v224, 32, v166
	s_nop 0
	v_addc_co_u32_e32 v131, vcc, 0, v129, vcc
	global_load_dwordx4 v[198:201], v[128:129], off
	global_load_dwordx4 v[202:205], v[128:129], off offset:256
	global_load_dwordx4 v[206:209], v[130:131], off
	global_load_dwordx4 v[210:213], v[130:131], off offset:256
	v_ashrrev_i32_e32 v225, 31, v224
	v_lshlrev_b64 v[128:129], 11, v[224:225]
	v_lshl_add_u64 v[128:129], v[168:169], 0, v[128:129]
	v_add_co_u32_e32 v130, vcc, s40, v128
	v_add_u32_e32 v170, 48, v166
	s_nop 0
	v_addc_co_u32_e32 v131, vcc, 0, v129, vcc
	global_load_dwordx4 v[214:217], v[128:129], off
	global_load_dwordx4 v[144:147], v[128:129], off offset:256
	global_load_dwordx4 v[218:221], v[130:131], off
	global_load_dwordx4 v[148:151], v[130:131], off offset:256
	v_ashrrev_i32_e32 v171, 31, v170
	v_lshlrev_b64 v[128:129], 11, v[170:171]
	v_lshl_add_u64 v[128:129], v[168:169], 0, v[128:129]
	v_lshlrev_b32_e32 v139, 7, v136
	v_bitop3_b32 v136, v136, v134, 7 bitop3:0x78
	v_add_co_u32_e32 v132, vcc, s40, v128
	v_lshlrev_b32_e32 v136, 4, v136
	s_nop 0
	v_addc_co_u32_e32 v133, vcc, 0, v129, vcc
	v_add3_u32 v178, s51, v139, v136
	v_and_b32_e32 v181, 1, v134
	global_load_dwordx4 v[136:139], v[128:129], off
	s_nop 0
	global_load_dwordx4 v[128:131], v[128:129], off offset:256
	s_nop 0
	global_load_dwordx4 v[140:143], v[132:133], off
	s_nop 0
	global_load_dwordx4 v[132:135], v[132:133], off offset:256
	ds_write_b128 v179, v[124:127]
	ds_write_b128 v180, v[120:123]
	ds_read_b128 v[120:123], v178
	ds_read_b128 v[124:127], v178 offset:1024
	v_cmp_eq_u32_e32 vcc, 0, v181
	v_lshlrev_b64 v[226:227], 12, v[166:167]
	v_lshl_add_u64 v[226:227], v[164:165], 0, v[226:227]
	s_waitcnt vmcnt(0)
	v_cndmask_b32_e32 v167, v184, v182, vcc
	v_cndmask_b32_e32 v181, v185, v183, vcc
	v_lshlrev_b32_e32 v182, 16, v167
	v_and_b32_e32 v183, 0xffff0000, v167
	v_lshlrev_b32_e32 v184, 16, v181
	v_and_b32_e32 v185, 0xffff0000, v181
	s_waitcnt lgkmcnt(1)
	v_pk_add_f32 v[120:121], v[120:121], v[182:183]
	v_cndmask_b32_e32 v186, v188, v186, vcc
	v_pk_add_f32 v[122:123], v[122:123], v[184:185]
	v_cndmask_b32_e32 v187, v189, v187, vcc
	global_store_dwordx4 v[226:227], v[120:123], off
	s_nop 1
	v_lshlrev_b32_e32 v120, 16, v186
	v_and_b32_e32 v121, 0xffff0000, v186
	v_lshlrev_b32_e32 v122, 16, v187
	v_and_b32_e32 v123, 0xffff0000, v187
	s_waitcnt lgkmcnt(0)
	v_pk_add_f32 v[120:121], v[124:125], v[120:121]
	v_add_co_u32_e64 v124, s[4:5], s47, v226
	v_pk_add_f32 v[122:123], v[126:127], v[122:123]
	s_nop 0
	v_addc_co_u32_e64 v125, s[4:5], 0, v227, s[4:5]
	global_store_dwordx4 v[124:125], v[120:123], off
	ds_write_b128 v179, v[116:119]
	ds_write_b128 v180, v[112:115]
	ds_read_b128 v[112:115], v178
	ds_read_b128 v[116:119], v178 offset:1024
	v_cndmask_b32_e32 v121, v192, v190, vcc
	v_cndmask_b32_e32 v123, v193, v191, vcc
	v_lshlrev_b32_e32 v120, 16, v121
	v_and_b32_e32 v121, 0xffff0000, v121
	v_lshlrev_b32_e32 v122, 16, v123
	v_and_b32_e32 v123, 0xffff0000, v123
	v_cndmask_b32_e32 v126, v196, v194, vcc
	v_cndmask_b32_e32 v127, v197, v195, vcc
	s_waitcnt lgkmcnt(1)
	v_pk_add_f32 v[112:113], v[112:113], v[120:121]
	v_pk_add_f32 v[114:115], v[114:115], v[122:123]
	global_store_dwordx4 v[226:227], v[112:115], off offset:512
	s_nop 1
	v_lshlrev_b32_e32 v112, 16, v126
	v_and_b32_e32 v113, 0xffff0000, v126
	v_lshlrev_b32_e32 v114, 16, v127
	v_and_b32_e32 v115, 0xffff0000, v127
	s_waitcnt lgkmcnt(0)
	v_pk_add_f32 v[112:113], v[116:117], v[112:113]
	v_pk_add_f32 v[114:115], v[118:119], v[114:115]
	global_store_dwordx4 v[124:125], v[112:115], off offset:512
	ds_write_b128 v179, v[108:111]
	ds_write_b128 v180, v[104:107]
	ds_read_b128 v[104:107], v178
	ds_read_b128 v[108:111], v178 offset:1024
	v_cndmask_b32_e32 v115, v200, v198, vcc
	v_cndmask_b32_e32 v117, v201, v199, vcc
	v_lshlrev_b64 v[112:113], 12, v[222:223]
	v_lshlrev_b32_e32 v114, 16, v115
	v_and_b32_e32 v115, 0xffff0000, v115
	v_lshlrev_b32_e32 v116, 16, v117
	v_and_b32_e32 v117, 0xffff0000, v117
	v_lshl_add_u64 v[112:113], v[164:165], 0, v[112:113]
	v_cndmask_b32_e32 v118, v208, v206, vcc
	s_waitcnt lgkmcnt(1)
; #define LAS __attribute__((address_space(3)))
;     __device__ __forceinline__ void operator()(const f32x4 (&acc)[2][2][4][2], const pg8::Unit& u, int wr, int wc, int fr, int fq) const {
;     ...
;             for (int m = 0; m < 4; ++m) {
;                 const size_t ro = (size_t)(128 * ai + 64 * wr + 16 * m + rr) * DM + cb;
; #pragma unroll
;                 for (int bj = 0; bj < 2; ++bj) {
;                     *(LAS f32x4*)(T + woff0) = acc[ai][bj][m][0]; *(LAS f32x4*)(T + woff1) = acc[ai][bj][m][1];
;                     const f32x4 a0 = *(const LAS f32x4*)(T + roff), a1 = *(const LAS f32x4*)(T + roff + 1024);
;                     const v4u t0 = xv[m][bj][0], t1 = xv[m][bj][1];
;                     const unsigned u0 = (p & 1) ? t0.z : t0.x, u1 = (p & 1) ? t0.w : t0.y, u2 = (p & 1) ? t1.z : t1.x, u3 = (p & 1) ? t1.w : t1.y;
;                     *(f32x4*)(ob + ro + 128 * bj) = (f32x4){bflo(u0), bfhi(u0), bflo(u1), bfhi(u1)} + a0; *(f32x4*)(ob + ro + 8 * DM + 128 * bj) = (f32x4){bflo(u2), bfhi(u2), bflo(u3), bfhi(u3)} + a1;
;                 }
	v_pk_add_f32 v[104:105], v[104:105], v[114:115]
	v_pk_add_f32 v[106:107], v[106:107], v[116:117]
	v_cndmask_b32_e32 v119, v209, v207, vcc
	global_store_dwordx4 v[112:113], v[104:107], off
	s_nop 1
	v_lshlrev_b32_e32 v104, 16, v118
	v_and_b32_e32 v105, 0xffff0000, v118
	v_lshlrev_b32_e32 v106, 16, v119
	v_and_b32_e32 v107, 0xffff0000, v119
	s_waitcnt lgkmcnt(0)
	v_pk_add_f32 v[104:105], v[108:109], v[104:105]
	v_add_co_u32_e64 v108, s[4:5], s47, v112
	v_pk_add_f32 v[106:107], v[110:111], v[106:107]
	s_nop 0
	v_addc_co_u32_e64 v109, s[4:5], 0, v113, s[4:5]
	global_store_dwordx4 v[108:109], v[104:107], off
	ds_write_b128 v179, v[100:103]
	ds_write_b128 v180, v[96:99]
	ds_read_b128 v[96:99], v178
	ds_read_b128 v[100:103], v178 offset:1024
	v_cndmask_b32_e32 v105, v204, v202, vcc
	v_cndmask_b32_e32 v107, v205, v203, vcc
	v_lshlrev_b32_e32 v104, 16, v105
	v_and_b32_e32 v105, 0xffff0000, v105
	v_lshlrev_b32_e32 v106, 16, v107
	v_and_b32_e32 v107, 0xffff0000, v107
	v_cndmask_b32_e32 v110, v212, v210, vcc
	v_cndmask_b32_e32 v111, v213, v211, vcc
	s_waitcnt lgkmcnt(1)
	v_pk_add_f32 v[96:97], v[96:97], v[104:105]
	v_pk_add_f32 v[98:99], v[98:99], v[106:107]
	global_store_dwordx4 v[112:113], v[96:99], off offset:512
	s_nop 1
	v_lshlrev_b32_e32 v96, 16, v110
	v_and_b32_e32 v97, 0xffff0000, v110
	v_lshlrev_b32_e32 v98, 16, v111
	v_and_b32_e32 v99, 0xffff0000, v111
	s_waitcnt lgkmcnt(0)
	v_pk_add_f32 v[96:97], v[100:101], v[96:97]
	v_pk_add_f32 v[98:99], v[102:103], v[98:99]
	global_store_dwordx4 v[108:109], v[96:99], off offset:512
	ds_write_b128 v179, v[92:95]
	ds_write_b128 v180, v[88:91]
	ds_read_b128 v[88:91], v178
	ds_read_b128 v[92:95], v178 offset:1024
	v_cndmask_b32_e32 v99, v216, v214, vcc
	v_cndmask_b32_e32 v101, v217, v215, vcc
	v_lshlrev_b64 v[96:97], 12, v[224:225]
	v_lshlrev_b32_e32 v98, 16, v99
	v_and_b32_e32 v99, 0xffff0000, v99
	v_lshlrev_b32_e32 v100, 16, v101
	v_and_b32_e32 v101, 0xffff0000, v101
	v_lshl_add_u64 v[96:97], v[164:165], 0, v[96:97]
	v_cndmask_b32_e32 v102, v220, v218, vcc
	s_waitcnt lgkmcnt(1)
	v_pk_add_f32 v[88:89], v[88:89], v[98:99]
	v_pk_add_f32 v[90:91], v[90:91], v[100:101]
	v_cndmask_b32_e32 v103, v221, v219, vcc
	global_store_dwordx4 v[96:97], v[88:91], off
	s_nop 1
	v_lshlrev_b32_e32 v88, 16, v102
	v_and_b32_e32 v89, 0xffff0000, v102
	v_lshlrev_b32_e32 v90, 16, v103
	v_and_b32_e32 v91, 0xffff0000, v103
	s_waitcnt lgkmcnt(0)
	v_pk_add_f32 v[88:89], v[92:93], v[88:89]
	v_add_co_u32_e64 v92, s[4:5], s47, v96
	v_pk_add_f32 v[90:91], v[94:95], v[90:91]
	s_nop 0
	v_addc_co_u32_e64 v93, s[4:5], 0, v97, s[4:5]
	global_store_dwordx4 v[92:93], v[88:91], off
	ds_write_b128 v179, v[84:87]
	ds_write_b128 v180, v[80:83]
	ds_read_b128 v[80:83], v178
	ds_read_b128 v[84:87], v178 offset:1024
	v_cndmask_b32_e32 v89, v146, v144, vcc
	v_cndmask_b32_e32 v91, v147, v145, vcc
	v_lshlrev_b32_e32 v88, 16, v89
	v_and_b32_e32 v89, 0xffff0000, v89
	v_lshlrev_b32_e32 v90, 16, v91
	v_and_b32_e32 v91, 0xffff0000, v91
	v_cndmask_b32_e32 v94, v150, v148, vcc
	v_cndmask_b32_e32 v95, v151, v149, vcc
	s_waitcnt lgkmcnt(1)
	v_pk_add_f32 v[80:81], v[80:81], v[88:89]
	v_pk_add_f32 v[82:83], v[82:83], v[90:91]
	global_store_dwordx4 v[96:97], v[80:83], off offset:512
	s_nop 1
	v_lshlrev_b32_e32 v80, 16, v94
	v_and_b32_e32 v81, 0xffff0000, v94
	v_lshlrev_b32_e32 v82, 16, v95
	v_and_b32_e32 v83, 0xffff0000, v95
	s_waitcnt lgkmcnt(0)
	v_pk_add_f32 v[80:81], v[84:85], v[80:81]
	v_pk_add_f32 v[82:83], v[86:87], v[82:83]
	global_store_dwordx4 v[92:93], v[80:83], off offset:512
	ds_write_b128 v179, v[76:79]
	ds_write_b128 v180, v[72:75]
	ds_read_b128 v[72:75], v178
	ds_read_b128 v[76:79], v178 offset:1024
	v_cndmask_b32_e32 v83, v138, v136, vcc
	v_cndmask_b32_e32 v85, v139, v137, vcc
	v_lshlrev_b64 v[80:81], 12, v[170:171]
	v_lshlrev_b32_e32 v82, 16, v83
	v_and_b32_e32 v83, 0xffff0000, v83
	v_lshlrev_b32_e32 v84, 16, v85
	v_and_b32_e32 v85, 0xffff0000, v85
	v_lshl_add_u64 v[80:81], v[164:165], 0, v[80:81]
	v_cndmask_b32_e32 v86, v142, v140, vcc
	s_waitcnt lgkmcnt(1)
	v_pk_add_f32 v[72:73], v[72:73], v[82:83]
	v_pk_add_f32 v[74:75], v[74:75], v[84:85]
	v_cndmask_b32_e32 v87, v143, v141, vcc
	global_store_dwordx4 v[80:81], v[72:75], off
	s_nop 1
	v_lshlrev_b32_e32 v72, 16, v86
	v_and_b32_e32 v73, 0xffff0000, v86
	v_lshlrev_b32_e32 v74, 16, v87
	v_and_b32_e32 v75, 0xffff0000, v87
	s_waitcnt lgkmcnt(0)
	v_pk_add_f32 v[72:73], v[76:77], v[72:73]
	v_add_co_u32_e64 v76, s[4:5], s47, v80
	v_pk_add_f32 v[74:75], v[78:79], v[74:75]
	s_nop 0
	v_addc_co_u32_e64 v77, s[4:5], 0, v81, s[4:5]
	global_store_dwordx4 v[76:77], v[72:75], off
	ds_write_b128 v179, v[68:71]
	ds_write_b128 v180, v[64:67]
	ds_read_b128 v[64:67], v178
	ds_read_b128 v[68:71], v178 offset:1024
	v_cndmask_b32_e32 v73, v130, v128, vcc
	v_cndmask_b32_e32 v75, v131, v129, vcc
	v_lshlrev_b32_e32 v72, 16, v73
	v_and_b32_e32 v73, 0xffff0000, v73
	v_lshlrev_b32_e32 v74, 16, v75
	v_and_b32_e32 v75, 0xffff0000, v75
	v_cndmask_b32_e32 v78, v134, v132, vcc
	v_cndmask_b32_e32 v79, v135, v133, vcc
	s_waitcnt lgkmcnt(1)
	v_pk_add_f32 v[64:65], v[64:65], v[72:73]
	v_pk_add_f32 v[66:67], v[66:67], v[74:75]
	global_store_dwordx4 v[80:81], v[64:67], off offset:512
	v_add_u32_e32 v130, 0x80, v166
	v_ashrrev_i32_e32 v131, 31, v130
	v_lshlrev_b32_e32 v64, 16, v78
	v_and_b32_e32 v65, 0xffff0000, v78
	v_lshlrev_b32_e32 v66, 16, v79
	v_and_b32_e32 v67, 0xffff0000, v79
	s_waitcnt lgkmcnt(0)
; #define LAS __attribute__((address_space(3)))
; #define NTLD(p) __builtin_nontemporal_load(p)
;     __device__ __forceinline__ void operator()(const f32x4 (&acc)[2][2][4][2], const pg8::Unit& u, int wr, int wc, int fr, int fq) const {
;     ...
;             v4u xv[4][2][2];
; #pragma unroll
;             for (int m = 0; m < 4; ++m) {
;                 const size_t ro = (size_t)(128 * ai + 64 * wr + 16 * m + rr) * DM + (cb & ~7);
; #pragma unroll
;                 for (int bj = 0; bj < 2; ++bj) { xv[m][bj][0] = NTLD((const v4u*)(xb + ro + 128 * bj)); xv[m][bj][1] = NTLD((const v4u*)(xb + ro + 8 * DM + 128 * bj)); }
;             }
; #pragma unroll
;             for (int m = 0; m < 4; ++m) {
;                 const size_t ro = (size_t)(128 * ai + 64 * wr + 16 * m + rr) * DM + cb;
; #pragma unroll
;                 for (int bj = 0; bj < 2; ++bj) {
;                     *(LAS f32x4*)(T + woff0) = acc[ai][bj][m][0]; *(LAS f32x4*)(T + woff1) = acc[ai][bj][m][1];
;                     const f32x4 a0 = *(const LAS f32x4*)(T + roff), a1 = *(const LAS f32x4*)(T + roff + 1024);
;                     const v4u t0 = xv[m][bj][0], t1 = xv[m][bj][1];
;                     const unsigned u0 = (p & 1) ? t0.z : t0.x, u1 = (p & 1) ? t0.w : t0.y, u2 = (p & 1) ? t1.z : t1.x, u3 = (p & 1) ? t1.w : t1.y;
;                     *(f32x4*)(ob + ro + 128 * bj) = (f32x4){bflo(u0), bfhi(u0), bflo(u1), bfhi(u1)} + a0; *(f32x4*)(ob + ro + 8 * DM + 128 * bj) = (f32x4){bflo(u2), bfhi(u2), bflo(u3), bfhi(u3)} + a1;
;                 }
	v_pk_add_f32 v[64:65], v[68:69], v[64:65]
	v_pk_add_f32 v[66:67], v[70:71], v[66:67]
	global_store_dwordx4 v[76:77], v[64:67], off offset:512
	v_add_u32_e32 v132, 0x90, v166
	v_ashrrev_i32_e32 v133, 31, v132
	v_lshlrev_b64 v[64:65], 11, v[130:131]
	v_lshl_add_u64 v[64:65], v[168:169], 0, v[64:65]
	global_load_dwordx4 v[82:85], v[64:65], off
	v_add_co_u32_e64 v66, s[4:5], s40, v64
	v_add_u32_e32 v134, 0xa0, v166
	s_nop 0
	v_addc_co_u32_e64 v67, s[4:5], 0, v65, s[4:5]
	global_load_dwordx4 v[86:89], v[66:67], off
	global_load_dwordx4 v[90:93], v[64:65], off offset:256
	global_load_dwordx4 v[94:97], v[66:67], off offset:256
	v_lshlrev_b64 v[64:65], 11, v[132:133]
	v_lshl_add_u64 v[64:65], v[168:169], 0, v[64:65]
	v_add_co_u32_e64 v66, s[4:5], s40, v64
	v_ashrrev_i32_e32 v135, 31, v134
	s_nop 0
	v_addc_co_u32_e64 v67, s[4:5], 0, v65, s[4:5]
	global_load_dwordx4 v[98:101], v[64:65], off
	global_load_dwordx4 v[102:105], v[64:65], off offset:256
	global_load_dwordx4 v[106:109], v[66:67], off
	global_load_dwordx4 v[110:113], v[66:67], off offset:256
	v_lshlrev_b64 v[64:65], 11, v[134:135]
	v_lshl_add_u64 v[64:65], v[168:169], 0, v[64:65]
	v_add_co_u32_e64 v66, s[4:5], s40, v64
	v_add_u32_e32 v80, 0xb0, v166
	s_nop 0
	v_addc_co_u32_e64 v67, s[4:5], 0, v65, s[4:5]
	global_load_dwordx4 v[114:117], v[64:65], off
	global_load_dwordx4 v[118:121], v[64:65], off offset:256
	global_load_dwordx4 v[122:125], v[66:67], off
	global_load_dwordx4 v[126:129], v[66:67], off offset:256
	v_ashrrev_i32_e32 v81, 31, v80
	v_lshlrev_b64 v[64:65], 11, v[80:81]
	v_lshl_add_u64 v[64:65], v[168:169], 0, v[64:65]
	v_add_co_u32_e64 v68, s[4:5], s40, v64
	v_lshlrev_b64 v[130:131], 12, v[130:131]
	s_nop 0
	v_addc_co_u32_e64 v69, s[4:5], 0, v65, s[4:5]
	global_load_dwordx4 v[72:75], v[64:65], off
	s_nop 0
	global_load_dwordx4 v[64:67], v[64:65], off offset:256
	s_nop 0
	global_load_dwordx4 v[76:79], v[68:69], off
	s_nop 0
	global_load_dwordx4 v[68:71], v[68:69], off offset:256
	ds_write_b128 v179, v[60:63]
	ds_write_b128 v180, v[56:59]
	ds_read_b128 v[56:59], v178
	ds_read_b128 v[60:63], v178 offset:1024
	v_lshl_add_u64 v[130:131], v[164:165], 0, v[130:131]
	s_waitcnt vmcnt(15)
	v_cndmask_b32_e32 v84, v84, v82, vcc
	v_cndmask_b32_e32 v85, v85, v83, vcc
	v_lshlrev_b32_e32 v82, 16, v84
	v_and_b32_e32 v83, 0xffff0000, v84
	v_lshlrev_b32_e32 v84, 16, v85
	v_and_b32_e32 v85, 0xffff0000, v85
	s_waitcnt vmcnt(14)
	v_cndmask_b32_e32 v86, v88, v86, vcc
	s_waitcnt lgkmcnt(1)
	v_pk_add_f32 v[56:57], v[56:57], v[82:83]
	v_pk_add_f32 v[58:59], v[58:59], v[84:85]
	v_cndmask_b32_e32 v87, v89, v87, vcc
	global_store_dwordx4 v[130:131], v[56:59], off
	s_nop 1
	v_lshlrev_b32_e32 v56, 16, v86
	v_and_b32_e32 v57, 0xffff0000, v86
	v_lshlrev_b32_e32 v58, 16, v87
	v_and_b32_e32 v59, 0xffff0000, v87
	s_waitcnt lgkmcnt(0)
	v_pk_add_f32 v[56:57], v[60:61], v[56:57]
	v_add_co_u32_e64 v60, s[4:5], s47, v130
	v_pk_add_f32 v[58:59], v[62:63], v[58:59]
	s_nop 0
	v_addc_co_u32_e64 v61, s[4:5], 0, v131, s[4:5]
	global_store_dwordx4 v[60:61], v[56:59], off
	ds_write_b128 v179, v[52:55]
	ds_write_b128 v180, v[48:51]
	ds_read_b128 v[48:51], v178
	ds_read_b128 v[52:55], v178 offset:1024
	s_waitcnt vmcnt(15)
	v_cndmask_b32_e32 v57, v92, v90, vcc
	v_cndmask_b32_e32 v59, v93, v91, vcc
	v_lshlrev_b32_e32 v56, 16, v57
	v_and_b32_e32 v57, 0xffff0000, v57
	v_lshlrev_b32_e32 v58, 16, v59
	v_and_b32_e32 v59, 0xffff0000, v59
	s_waitcnt vmcnt(14)
	v_cndmask_b32_e32 v62, v96, v94, vcc
	v_cndmask_b32_e32 v63, v97, v95, vcc
	s_waitcnt lgkmcnt(1)
	v_pk_add_f32 v[48:49], v[48:49], v[56:57]
	v_pk_add_f32 v[50:51], v[50:51], v[58:59]
	global_store_dwordx4 v[130:131], v[48:51], off offset:512
	s_nop 1
	v_lshlrev_b32_e32 v48, 16, v62
	v_and_b32_e32 v49, 0xffff0000, v62
	v_lshlrev_b32_e32 v50, 16, v63
	v_and_b32_e32 v51, 0xffff0000, v63
	s_waitcnt lgkmcnt(0)
	v_pk_add_f32 v[48:49], v[52:53], v[48:49]
	v_pk_add_f32 v[50:51], v[54:55], v[50:51]
	global_store_dwordx4 v[60:61], v[48:51], off offset:512
	ds_write_b128 v179, v[44:47]
	ds_write_b128 v180, v[40:43]
	ds_read_b128 v[40:43], v178
	ds_read_b128 v[44:47], v178 offset:1024
	s_waitcnt vmcnt(15)
	v_cndmask_b32_e32 v51, v100, v98, vcc
	v_cndmask_b32_e32 v53, v101, v99, vcc
	v_lshlrev_b64 v[48:49], 12, v[132:133]
	v_lshlrev_b32_e32 v50, 16, v51
	v_and_b32_e32 v51, 0xffff0000, v51
	v_lshlrev_b32_e32 v52, 16, v53
	v_and_b32_e32 v53, 0xffff0000, v53
	v_lshl_add_u64 v[48:49], v[164:165], 0, v[48:49]
	s_waitcnt vmcnt(13)
	v_cndmask_b32_e32 v54, v108, v106, vcc
	s_waitcnt lgkmcnt(1)
	v_pk_add_f32 v[40:41], v[40:41], v[50:51]
	v_pk_add_f32 v[42:43], v[42:43], v[52:53]
	v_cndmask_b32_e32 v55, v109, v107, vcc
	global_store_dwordx4 v[48:49], v[40:43], off
	s_nop 1
	v_lshlrev_b32_e32 v40, 16, v54
	v_and_b32_e32 v41, 0xffff0000, v54
	v_lshlrev_b32_e32 v42, 16, v55
	v_and_b32_e32 v43, 0xffff0000, v55
	s_waitcnt lgkmcnt(0)
; #define PG8_BAR __builtin_amdgcn_s_barrier()
; #define LAS __attribute__((address_space(3)))
; template <class Epi, class Sched, bool ALIGN_EPI = false, bool SP2 = false>
; __device__ __forceinline__ void gemm_phase(PG8_LAS unsigned char* lds, const Gemm g, const Sched& S, const Epi& E) {
;     ...
;         if (!has_next) break;
; #pragma unroll
;         for (int a = 0; a < 2; ++a)
; #pragma unroll
;             for (int b = 0; b < 2; ++b)
; #pragma unroll
;                 for (int m = 0; m < 4; ++m)
; #pragma unroll
;                     for (int n = 0; n < 2; ++n) acc[a][b][m][n] = (f32x4){0.f, 0.f, 0.f, 0.f};
;         cur = nxt; cA = nA; cB = nB; ++ui;
;         if constexpr (ALIGN_EPI) { if (wr == 1) PG8_BAR; }
;     __device__ __forceinline__ void operator()(const f32x4 (&acc)[2][2][4][2], const pg8::Unit& u, int wr, int wc, int fr, int fq) const {
;     ...
;             for (int m = 0; m < 4; ++m) {
;                 const size_t ro = (size_t)(128 * ai + 64 * wr + 16 * m + rr) * DM + cb;
; #pragma unroll
;                 for (int bj = 0; bj < 2; ++bj) {
;                     *(LAS f32x4*)(T + woff0) = acc[ai][bj][m][0]; *(LAS f32x4*)(T + woff1) = acc[ai][bj][m][1];
;                     const f32x4 a0 = *(const LAS f32x4*)(T + roff), a1 = *(const LAS f32x4*)(T + roff + 1024);
;                     const v4u t0 = xv[m][bj][0], t1 = xv[m][bj][1];
;                     const unsigned u0 = (p & 1) ? t0.z : t0.x, u1 = (p & 1) ? t0.w : t0.y, u2 = (p & 1) ? t1.z : t1.x, u3 = (p & 1) ? t1.w : t1.y;
;                     *(f32x4*)(ob + ro + 128 * bj) = (f32x4){bflo(u0), bfhi(u0), bflo(u1), bfhi(u1)} + a0; *(f32x4*)(ob + ro + 8 * DM + 128 * bj) = (f32x4){bflo(u2), bfhi(u2), bflo(u3), bfhi(u3)} + a1;
;                 }
	v_pk_add_f32 v[40:41], v[44:45], v[40:41]
	v_add_co_u32_e64 v44, s[4:5], s47, v48
	v_pk_add_f32 v[42:43], v[46:47], v[42:43]
	s_nop 0
	v_addc_co_u32_e64 v45, s[4:5], 0, v49, s[4:5]
	global_store_dwordx4 v[44:45], v[40:43], off
	ds_write_b128 v179, v[36:39]
	ds_write_b128 v180, v[32:35]
	ds_read_b128 v[32:35], v178
	ds_read_b128 v[36:39], v178 offset:1024
	v_cndmask_b32_e32 v41, v104, v102, vcc
	v_cndmask_b32_e32 v43, v105, v103, vcc
	v_lshlrev_b32_e32 v40, 16, v41
	v_and_b32_e32 v41, 0xffff0000, v41
	v_lshlrev_b32_e32 v42, 16, v43
	v_and_b32_e32 v43, 0xffff0000, v43
	s_waitcnt vmcnt(14)
	v_cndmask_b32_e32 v46, v112, v110, vcc
	v_cndmask_b32_e32 v47, v113, v111, vcc
	s_waitcnt lgkmcnt(1)
	v_pk_add_f32 v[32:33], v[32:33], v[40:41]
	v_pk_add_f32 v[34:35], v[34:35], v[42:43]
	global_store_dwordx4 v[48:49], v[32:35], off offset:512
	s_nop 1
	v_lshlrev_b32_e32 v32, 16, v46
	v_and_b32_e32 v33, 0xffff0000, v46
	v_lshlrev_b32_e32 v34, 16, v47
	v_and_b32_e32 v35, 0xffff0000, v47
	s_waitcnt lgkmcnt(0)
	v_pk_add_f32 v[32:33], v[36:37], v[32:33]
	v_pk_add_f32 v[34:35], v[38:39], v[34:35]
	global_store_dwordx4 v[44:45], v[32:35], off offset:512
	ds_write_b128 v179, v[28:31]
	ds_write_b128 v180, v[24:27]
	ds_read_b128 v[24:27], v178
	ds_read_b128 v[28:31], v178 offset:1024
	s_waitcnt vmcnt(15)
	v_cndmask_b32_e32 v35, v116, v114, vcc
	v_cndmask_b32_e32 v37, v117, v115, vcc
	v_lshlrev_b64 v[32:33], 12, v[134:135]
	v_lshlrev_b32_e32 v34, 16, v35
	v_and_b32_e32 v35, 0xffff0000, v35
	v_lshlrev_b32_e32 v36, 16, v37
	v_and_b32_e32 v37, 0xffff0000, v37
	v_lshl_add_u64 v[32:33], v[164:165], 0, v[32:33]
	s_waitcnt vmcnt(13)
	v_cndmask_b32_e32 v38, v124, v122, vcc
	s_waitcnt lgkmcnt(1)
	v_pk_add_f32 v[24:25], v[24:25], v[34:35]
	v_pk_add_f32 v[26:27], v[26:27], v[36:37]
	v_cndmask_b32_e32 v39, v125, v123, vcc
	global_store_dwordx4 v[32:33], v[24:27], off
	s_nop 1
	v_lshlrev_b32_e32 v24, 16, v38
	v_and_b32_e32 v25, 0xffff0000, v38
	v_lshlrev_b32_e32 v26, 16, v39
	v_and_b32_e32 v27, 0xffff0000, v39
	s_waitcnt lgkmcnt(0)
	v_pk_add_f32 v[24:25], v[28:29], v[24:25]
	v_add_co_u32_e64 v28, s[4:5], s47, v32
	v_pk_add_f32 v[26:27], v[30:31], v[26:27]
	s_nop 0
	v_addc_co_u32_e64 v29, s[4:5], 0, v33, s[4:5]
	global_store_dwordx4 v[28:29], v[24:27], off
	ds_write_b128 v179, v[20:23]
	ds_write_b128 v180, v[16:19]
	ds_read_b128 v[16:19], v178
	ds_read_b128 v[20:23], v178 offset:1024
	v_cndmask_b32_e32 v25, v120, v118, vcc
	v_cndmask_b32_e32 v27, v121, v119, vcc
	v_lshlrev_b32_e32 v24, 16, v25
	v_and_b32_e32 v25, 0xffff0000, v25
	v_lshlrev_b32_e32 v26, 16, v27
	v_and_b32_e32 v27, 0xffff0000, v27
	s_waitcnt vmcnt(14)
	v_cndmask_b32_e32 v30, v128, v126, vcc
	v_cndmask_b32_e32 v31, v129, v127, vcc
	s_waitcnt lgkmcnt(1)
	v_pk_add_f32 v[16:17], v[16:17], v[24:25]
	v_pk_add_f32 v[18:19], v[18:19], v[26:27]
	global_store_dwordx4 v[32:33], v[16:19], off offset:512
	s_nop 1
	v_lshlrev_b32_e32 v16, 16, v30
	v_and_b32_e32 v17, 0xffff0000, v30
	v_lshlrev_b32_e32 v18, 16, v31
	v_and_b32_e32 v19, 0xffff0000, v31
	s_waitcnt lgkmcnt(0)
	v_pk_add_f32 v[16:17], v[20:21], v[16:17]
	v_pk_add_f32 v[18:19], v[22:23], v[18:19]
	global_store_dwordx4 v[28:29], v[16:19], off offset:512
	ds_write_b128 v179, v[12:15]
	ds_write_b128 v180, v[8:11]
	ds_read_b128 v[8:11], v178
	ds_read_b128 v[12:15], v178 offset:1024
	s_waitcnt vmcnt(15)
	v_cndmask_b32_e32 v19, v74, v72, vcc
	v_cndmask_b32_e32 v21, v75, v73, vcc
	v_lshlrev_b64 v[16:17], 12, v[80:81]
	v_lshlrev_b32_e32 v18, 16, v19
	v_and_b32_e32 v19, 0xffff0000, v19
	v_lshlrev_b32_e32 v20, 16, v21
	v_and_b32_e32 v21, 0xffff0000, v21
	v_lshl_add_u64 v[16:17], v[164:165], 0, v[16:17]
	s_waitcnt vmcnt(13)
	v_cndmask_b32_e32 v22, v78, v76, vcc
	s_waitcnt lgkmcnt(1)
	v_pk_add_f32 v[8:9], v[8:9], v[18:19]
	v_pk_add_f32 v[10:11], v[10:11], v[20:21]
	v_cndmask_b32_e32 v23, v79, v77, vcc
	global_store_dwordx4 v[16:17], v[8:11], off
	s_nop 1
	v_lshlrev_b32_e32 v8, 16, v22
	v_and_b32_e32 v9, 0xffff0000, v22
	v_lshlrev_b32_e32 v10, 16, v23
	v_and_b32_e32 v11, 0xffff0000, v23
	s_waitcnt lgkmcnt(0)
	v_pk_add_f32 v[8:9], v[12:13], v[8:9]
	v_add_co_u32_e64 v12, s[4:5], s47, v16
	v_pk_add_f32 v[10:11], v[14:15], v[10:11]
	s_nop 0
	v_addc_co_u32_e64 v13, s[4:5], 0, v17, s[4:5]
	global_store_dwordx4 v[12:13], v[8:11], off
	ds_write_b128 v179, v[4:7]
	ds_write_b128 v180, v[0:3]
	ds_read_b128 v[0:3], v178
	ds_read_b128 v[4:7], v178 offset:1024
	v_cndmask_b32_e32 v9, v66, v64, vcc
	v_cndmask_b32_e32 v11, v67, v65, vcc
	v_lshlrev_b32_e32 v8, 16, v9
	v_and_b32_e32 v9, 0xffff0000, v9
	v_lshlrev_b32_e32 v10, 16, v11
	v_and_b32_e32 v11, 0xffff0000, v11
	s_waitcnt vmcnt(14)
	v_cndmask_b32_e32 v14, v70, v68, vcc
	v_cndmask_b32_e32 v15, v71, v69, vcc
	s_waitcnt lgkmcnt(1)
	v_pk_add_f32 v[0:1], v[0:1], v[8:9]
	v_pk_add_f32 v[2:3], v[2:3], v[10:11]
	global_store_dwordx4 v[16:17], v[0:3], off offset:512
	s_andn2_b64 vcc, exec, s[0:1]
	s_mov_b64 s[0:1], -1
	v_lshlrev_b32_e32 v0, 16, v14
	v_and_b32_e32 v1, 0xffff0000, v14
	v_lshlrev_b32_e32 v2, 16, v15
	v_and_b32_e32 v3, 0xffff0000, v15
	s_waitcnt lgkmcnt(0)
	v_pk_add_f32 v[0:1], v[4:5], v[0:1]
	v_pk_add_f32 v[2:3], v[6:7], v[2:3]
	global_store_dwordx4 v[12:13], v[0:3], off offset:512
	s_cbranch_vccnz .LBB0_1228
	s_andn2_b64 vcc, exec, s[8:9]
	s_cbranch_vccnz .LBB0_1227
	s_barrier
	s_branch .LBB0_1227
